# main grid barrier: poll loops spin without s_sleep 1 (registration wait, non-leader flag poll, leader flag poll)
# speedup vs baseline: 1.0025x; 1.0020x over previous
; DI unsigned xb_ld(unsigned* p) { return __hip_atomic_load(p, __ATOMIC_RELAXED, __HIP_MEMORY_SCOPE_AGENT); }
; DI void xcd_barrier_complete(unsigned* bar, unsigned x, unsigned& nloc, unsigned& nx) {
;     ...
;   for (;;) {
;     sum = 0u; cnt = 0u; mine = 0u;
; #pragma unroll
;     for (unsigned j = 0; j < 16; ++j) { const unsigned c = xb_ld(&bar[XB_XCNT(j)]); sum += c; cnt += (c > 0u) ? 1u : 0u; mine = (j == x) ? c : mine; }
;     if (sum == G) break;
;     __builtin_amdgcn_s_sleep(1);
;   }
.LBB0_888:
	global_load_dword v16, v1, s[14:15] sc1
	s_waitcnt lgkmcnt(0)
	global_load_dword v0, v1, s[18:19] sc1
	global_load_dword v2, v1, s[20:21] sc1
	global_load_dword v3, v1, s[22:23] sc1
	global_load_dword v4, v1, s[24:25] sc1
	global_load_dword v5, v1, s[26:27] sc1
	global_load_dword v6, v1, s[28:29] sc1
	global_load_dword v7, v1, s[30:31] sc1
	global_load_dword v8, v1, s[34:35] sc1
	global_load_dword v9, v1, s[36:37] sc1
	global_load_dword v10, v1, s[38:39] sc1
	global_load_dword v11, v1, s[40:41] sc1
	global_load_dword v12, v1, s[42:43] sc1
	global_load_dword v13, v1, s[44:45] sc1
	global_load_dword v14, v1, s[46:47] sc1
	global_load_dword v15, v1, s[48:49] sc1
	s_mov_b64 s[2:3], -1
	s_waitcnt vmcnt(14)
	v_add_u32_e32 v17, v0, v16
	s_waitcnt vmcnt(13)
	v_add_u32_e32 v17, v17, v2
	s_waitcnt vmcnt(12)
	v_add_u32_e32 v17, v17, v3
	s_waitcnt vmcnt(11)
	v_add_u32_e32 v17, v17, v4
	s_waitcnt vmcnt(10)
	v_add_u32_e32 v17, v17, v5
	s_waitcnt vmcnt(9)
	v_add_u32_e32 v17, v17, v6
	s_waitcnt vmcnt(8)
	v_add_u32_e32 v17, v17, v7
	s_waitcnt vmcnt(7)
	v_add_u32_e32 v17, v17, v8
	s_waitcnt vmcnt(6)
	v_add_u32_e32 v17, v17, v9
	s_waitcnt vmcnt(5)
	v_add_u32_e32 v17, v17, v10
	s_waitcnt vmcnt(4)
	v_add_u32_e32 v17, v17, v11
	s_waitcnt vmcnt(3)
	v_add_u32_e32 v17, v17, v12
	s_waitcnt vmcnt(2)
	v_add_u32_e32 v17, v17, v13
	s_waitcnt vmcnt(1)
	v_add_u32_e32 v17, v17, v14
	s_waitcnt vmcnt(0)
	v_add_u32_e32 v17, v17, v15
	v_cmp_eq_u32_e32 vcc, s55, v17
	s_cbranch_vccnz .LBB0_887
	s_mov_b64 s[2:3], 0
	s_branch .LBB0_887

; DI unsigned xb_ld(unsigned* p) { return __hip_atomic_load(p, __ATOMIC_RELAXED, __HIP_MEMORY_SCOPE_AGENT); }
; DI void xcd_barrier(const XcdBarrier& b) {
;     ...
;       else { while (xb_ld(&bar[XB_TOPGEN]) == tg) __builtin_amdgcn_s_sleep(1); }
;     ...
;       while (xb_ld(&bar[XB_XGEN(bx)]) == gen) __builtin_amdgcn_s_sleep(1);
.LBB0_896:
	global_load_dword v0, v1, s[4:5] sc1
	s_waitcnt vmcnt(0)
	v_cmp_ne_u32_e32 vcc, v0, v3
	s_or_b64 s[8:9], vcc, s[8:9]
	s_andn2_b64 exec, exec, s[8:9]
	s_cbranch_execnz .LBB0_896

; DI unsigned xb_ld(unsigned* p) { return __hip_atomic_load(p, __ATOMIC_RELAXED, __HIP_MEMORY_SCOPE_AGENT); }
; DI void xcd_barrier(const XcdBarrier& b) {
;     ...
;       else { while (xb_ld(&bar[XB_TOPGEN]) == tg) __builtin_amdgcn_s_sleep(1); }
;     ...
;       while (xb_ld(&bar[XB_XGEN(bx)]) == gen) __builtin_amdgcn_s_sleep(1);
.LBB0_904:
	global_load_dword v0, v1, s[50:51] sc1
	s_waitcnt vmcnt(0)
	v_cmp_ne_u32_e32 vcc, v0, v2
	s_or_b64 s[6:7], vcc, s[6:7]
	s_andn2_b64 exec, exec, s[6:7]
	s_cbranch_execnz .LBB0_904
